# drop redundant L1 invalidates after counter polls (LN exchange, LRU look-back); one wait for the four LN slot loads
# speedup vs baseline: 1.0032x; 1.0032x over previous
.LBB0_734:
.LBB0_735:
	s_or_b64 exec, exec, s[28:29]
	v_or_b32_e32 v0, s53, v115
	v_or_b32_e32 v46, s82, v0
	v_ashrrev_i32_e32 v47, 31, v46
	v_lshl_add_u64 v[46:47], v[46:47], 2, s[72:73]
	s_waitcnt vmcnt(0) lgkmcnt(0)
	s_waitcnt lgkmcnt(0)
	s_barrier
	global_load_dword v80, v[46:47], off
	v_or_b32_e32 v46, s84, v0
	v_ashrrev_i32_e32 v47, 31, v46
	v_lshl_add_u64 v[46:47], v[46:47], 2, s[72:73]
	global_load_dword v81, v[46:47], off
	v_lshlrev_b64 v[46:47], 3, v[0:1]
	v_lshl_add_u64 v[48:49], s[86:87], 0, v[46:47]
	v_lshl_add_u64 v[68:69], s[64:65], 0, v[46:47]
	flat_load_dwordx2 v[66:67], v[48:49] sc1
	v_lshl_add_u64 v[70:71], s[2:3], 0, v[46:47]
	flat_load_dwordx2 v[68:69], v[68:69] sc1
	s_waitcnt vmcnt(0) lgkmcnt(0)
	v_lshl_add_u64 v[68:69], s[74:75], 0, v[46:47]
	flat_load_dwordx2 v[68:69], v[68:69] sc1
	v_lshl_add_u64 v[72:73], s[88:89], 0, v[46:47]
	v_lshl_add_u64 v[74:75], s[60:61], 0, v[46:47]
	v_lshl_add_u64 v[76:77], s[56:57], 0, v[46:47]
	v_lshl_add_u64 v[46:47], s[58:59], 0, v[46:47]
	flat_load_dwordx2 v[70:71], v[70:71] sc1
	v_fmac_f32_e32 v67, v80, v66
	flat_load_dwordx2 v[72:73], v[72:73] sc1
	v_cndmask_b32_e64 v66, v67, v80, s[18:19]
	flat_load_dwordx2 v[74:75], v[74:75] sc1
	s_waitcnt vmcnt(0) lgkmcnt(0)
	v_fmac_f32_e32 v69, v66, v68
	flat_load_dwordx2 v[78:79], v[76:77] sc1
	v_cndmask_b32_e64 v66, v66, v69, s[20:21]
	flat_load_dwordx2 v[46:47], v[46:47] sc1
	v_lshl_add_u64 v[68:69], v[0:1], 0, s[82:83]
	v_lshl_add_u64 v[68:69], v[68:69], 2, s[72:73]
	s_waitcnt lgkmcnt(0)
	global_load_dword v78, v[68:69], off offset:64
	v_lshl_add_u64 v[68:69], v[0:1], 0, s[84:85]
	v_mov_b32_e32 v67, v1
	v_lshl_add_u64 v[68:69], v[68:69], 2, s[72:73]
	v_fmac_f32_e32 v73, v66, v72
	s_waitcnt vmcnt(0)
	v_fmac_f32_e32 v47, v81, v46
	v_cndmask_b32_e64 v46, v47, v81, s[22:23]
	v_cndmask_b32_e64 v47, v66, v73, s[22:23]
	v_or_b32_e32 v66, 16, v0
	v_fmac_f32_e32 v75, v46, v74
	v_lshlrev_b64 v[66:67], 3, v[66:67]
	v_cndmask_b32_e64 v46, v46, v75, s[24:25]
	global_load_dword v0, v[68:69], off offset:64
	v_lshl_add_u64 v[68:69], s[64:65], 0, v[66:67]
	v_fmac_f32_e32 v71, v46, v70
	flat_load_dwordx2 v[48:49], v[48:49] offset:128 sc1
	v_cndmask_b32_e64 v46, v46, v71, s[18:19]
	flat_load_dwordx2 v[68:69], v[68:69] sc1
	s_waitcnt vmcnt(0) lgkmcnt(0)
	v_lshl_add_u64 v[68:69], s[74:75], 0, v[66:67]
	v_lshl_add_u64 v[70:71], s[2:3], 0, v[66:67]
	v_lshl_add_u64 v[72:73], s[88:89], 0, v[66:67]
	v_lshl_add_u64 v[74:75], s[60:61], 0, v[66:67]
	v_lshl_add_u64 v[66:67], s[58:59], 0, v[66:67]
	flat_load_dwordx2 v[68:69], v[68:69] sc1
	v_fmac_f32_e32 v49, v78, v48
	flat_load_dwordx2 v[70:71], v[70:71] sc1
	v_cndmask_b32_e64 v48, v49, v78, s[18:19]
	flat_load_dwordx2 v[72:73], v[72:73] sc1
	s_nop 0
	flat_load_dwordx2 v[74:75], v[74:75] sc1
	s_nop 0
	flat_load_dwordx2 v[76:77], v[76:77] offset:128 sc1
	s_waitcnt vmcnt(0) lgkmcnt(0)
	v_fmac_f32_e32 v69, v48, v68
	flat_load_dwordx2 v[66:67], v[66:67] sc1
	v_cndmask_b32_e64 v48, v48, v69, s[20:21]
	v_fmac_f32_e32 v73, v48, v72
	v_cndmask_b32_e64 v48, v48, v73, s[22:23]
	s_waitcnt vmcnt(0) lgkmcnt(0)
	v_fmac_f32_e32 v67, v0, v66
	v_cndmask_b32_e64 v0, v67, v0, s[22:23]
	v_fmac_f32_e32 v75, v0, v74
	v_cndmask_b32_e64 v0, v0, v75, s[24:25]
	v_fmac_f32_e32 v71, v0, v70
	v_cndmask_b32_e64 v0, v0, v71, s[18:19]

.LBB0_943:
.LBB0_944:
	s_waitcnt vmcnt(0) lgkmcnt(0)
	s_barrier
	s_and_saveexec_b64 s[2:3], s[12:13]
	s_cbranch_execz .LBB0_946
	v_lshlrev_b64 v[2:3], 5, v[2:3]
	v_lshl_add_u64 v[2:3], s[4:5], 0, v[2:3]
	flat_load_dwordx2 v[6:7], v[2:3] sc1
	flat_load_dwordx2 v[8:9], v[2:3] offset:8 sc1
	flat_load_dwordx2 v[10:11], v[2:3] offset:16 sc1
	flat_load_dwordx2 v[14:15], v[2:3] offset:24 sc1
	s_waitcnt vmcnt(0) lgkmcnt(0)
	v_add_f32_e32 v0, 0, v6
	v_add_f32_e32 v0, v0, v8
	v_add_f32_e32 v0, v0, v10
	v_add_f32_e32 v0, v0, v14
	v_fmamk_f32 v5, v0, 0xbe800000, v6
	v_mul_f32_e32 v6, 0x43800000, v5
	v_fmac_f32_e32 v7, v5, v6
	v_fmamk_f32 v6, v0, 0xbe800000, v8
	v_add_f32_e32 v5, 0, v7
	v_mul_f32_e32 v7, 0x43800000, v6
	v_fmac_f32_e32 v9, v6, v7
	v_fmamk_f32 v6, v0, 0xbe800000, v10
	v_mul_f32_e32 v12, 0x3e800000, v0
	v_mul_f32_e32 v7, 0x43800000, v6
	v_fmamk_f32 v0, v0, 0xbe800000, v14
	v_add_f32_e32 v5, v9, v5
	v_fmac_f32_e32 v11, v6, v7
	v_mul_f32_e32 v2, 0x43800000, v0
	v_add_f32_e32 v5, v11, v5
	v_fmac_f32_e32 v15, v0, v2
	v_add_f32_e32 v0, v15, v5
	v_mov_b32_e32 v2, 0x3727c5ac
	v_fmamk_f32 v0, v0, 0x3a800000, v2
	v_rsq_f32_e32 v13, v0
	v_lshl_add_u32 v0, v4, 3, 0
	ds_write_b64 v0, v[12:13] offset:8192
